# RWKV chunk-chain step (64x64x64 f32 matmul per chunk): inner loop fully unrolled, LDS operand reads software-pipelined over spare VGPRs with counted lgkmcnt (about 14 reads in flight)
# speedup vs baseline: 1.0877x; 1.0008x over previous
; __device__ __forceinline__ void chain_item(PP p, int jl, int sh, char* smem) {
;     ...
; #pragma unroll 8
;         for (int j0 = 0; j0 < 64; ++j0) {
;             const float sv = Sl[i * 65 + j0];
;             const f32x4 v0 = *(const f32x4*)(Pl + j0 * 64 + jq * 8), v1 = *(const f32x4*)(Pl + j0 * 64 + jq * 8 + 4);
;             acc[0] += sv * v0.x; acc[1] += sv * v0.y; acc[2] += sv * v0.z; acc[3] += sv * v0.w;
;             acc[4] += sv * v1.x; acc[5] += sv * v1.y; acc[6] += sv * v1.z; acc[7] += sv * v1.w;
;         }
.LBB0_1739:
	v_add_u32_e32 v44, s8, v5
	ds_read2_b32 v[42:43], v44 offset1:1
	ds_read_b128 v[26:29], v41
	ds_read_b128 v[30:33], v41 offset:16
	ds_read_b128 v[194:197], v41 offset:256
	ds_read_b128 v[198:201], v41 offset:272
	ds_read2_b32 v[46:47], v44 offset0:2 offset1:3
	ds_read_b128 v[202:205], v41 offset:512
	ds_read_b128 v[206:209], v41 offset:528
	ds_read_b128 v[210:213], v41 offset:768
	ds_read_b128 v[214:217], v41 offset:784
	ds_read2_b32 v[48:49], v44 offset0:4 offset1:5
	ds_read_b128 v[218:221], v41 offset:1024
	ds_read_b128 v[222:225], v41 offset:1040
	ds_read_b128 v[226:229], v41 offset:1280
	s_waitcnt lgkmcnt(13)
	ds_read_b128 v[230:233], v41 offset:1296
	s_waitcnt lgkmcnt(13)
	ds_read2_b32 v[50:51], v44 offset0:6 offset1:7
	v_pk_fma_f32 v[26:27], v[42:43], v[26:27], v[18:19] op_sel_hi:[0,1,1]
	v_pk_fma_f32 v[28:29], v[42:43], v[28:29], v[20:21] op_sel_hi:[0,1,1]
	s_waitcnt lgkmcnt(13)
	ds_read_b128 v[18:21], v41 offset:1536
	v_pk_fma_f32 v[30:31], v[42:43], v[30:31], v[22:23] op_sel_hi:[0,1,1]
	v_pk_fma_f32 v[32:33], v[42:43], v[32:33], v[24:25] op_sel_hi:[0,1,1]
	s_waitcnt lgkmcnt(13)
	ds_read_b128 v[22:25], v41 offset:1552
	v_pk_fma_f32 v[26:27], v[42:43], v[194:195], v[26:27] op_sel:[1,0,0]
	v_pk_fma_f32 v[28:29], v[42:43], v[196:197], v[28:29] op_sel:[1,0,0]
	s_waitcnt lgkmcnt(13)
	ds_read_b128 v[194:197], v41 offset:1792
	v_pk_fma_f32 v[30:31], v[42:43], v[198:199], v[30:31] op_sel:[1,0,0]
	v_pk_fma_f32 v[32:33], v[42:43], v[200:201], v[32:33] op_sel:[1,0,0]
	s_waitcnt lgkmcnt(13)
	ds_read_b128 v[198:201], v41 offset:1808
	s_waitcnt lgkmcnt(13)
	ds_read2_b32 v[42:43], v44 offset0:8 offset1:9
	v_pk_fma_f32 v[26:27], v[46:47], v[202:203], v[26:27] op_sel_hi:[0,1,1]
	v_pk_fma_f32 v[28:29], v[46:47], v[204:205], v[28:29] op_sel_hi:[0,1,1]
	s_waitcnt lgkmcnt(13)
	ds_read_b128 v[202:205], v41 offset:2048
	v_pk_fma_f32 v[30:31], v[46:47], v[206:207], v[30:31] op_sel_hi:[0,1,1]
	v_pk_fma_f32 v[32:33], v[46:47], v[208:209], v[32:33] op_sel_hi:[0,1,1]
	s_waitcnt lgkmcnt(13)
	ds_read_b128 v[206:209], v41 offset:2064
	v_pk_fma_f32 v[26:27], v[46:47], v[210:211], v[26:27] op_sel:[1,0,0]
	v_pk_fma_f32 v[28:29], v[46:47], v[212:213], v[28:29] op_sel:[1,0,0]
	s_waitcnt lgkmcnt(13)
	ds_read_b128 v[210:213], v41 offset:2304
	v_pk_fma_f32 v[30:31], v[46:47], v[214:215], v[30:31] op_sel:[1,0,0]
	v_pk_fma_f32 v[32:33], v[46:47], v[216:217], v[32:33] op_sel:[1,0,0]
	s_waitcnt lgkmcnt(13)
	ds_read_b128 v[214:217], v41 offset:2320
	s_waitcnt lgkmcnt(13)
	ds_read2_b32 v[52:53], v44 offset0:10 offset1:11
	v_pk_fma_f32 v[26:27], v[48:49], v[218:219], v[26:27] op_sel_hi:[0,1,1]
	v_pk_fma_f32 v[28:29], v[48:49], v[220:221], v[28:29] op_sel_hi:[0,1,1]
	s_waitcnt lgkmcnt(13)
	ds_read_b128 v[218:221], v41 offset:2560
	v_pk_fma_f32 v[30:31], v[48:49], v[222:223], v[30:31] op_sel_hi:[0,1,1]
	v_pk_fma_f32 v[32:33], v[48:49], v[224:225], v[32:33] op_sel_hi:[0,1,1]
	s_waitcnt lgkmcnt(13)
	ds_read_b128 v[222:225], v41 offset:2576
	v_pk_fma_f32 v[26:27], v[48:49], v[226:227], v[26:27] op_sel:[1,0,0]
	v_pk_fma_f32 v[28:29], v[48:49], v[228:229], v[28:29] op_sel:[1,0,0]
	s_waitcnt lgkmcnt(13)
	ds_read_b128 v[226:229], v41 offset:2816
	v_pk_fma_f32 v[30:31], v[48:49], v[230:231], v[30:31] op_sel:[1,0,0]
	v_pk_fma_f32 v[32:33], v[48:49], v[232:233], v[32:33] op_sel:[1,0,0]
	s_waitcnt lgkmcnt(13)
	ds_read_b128 v[230:233], v41 offset:2832
	s_waitcnt lgkmcnt(13)
	ds_read2_b32 v[46:47], v44 offset0:12 offset1:13
	v_pk_fma_f32 v[26:27], v[50:51], v[18:19], v[26:27] op_sel_hi:[0,1,1]
	v_pk_fma_f32 v[28:29], v[50:51], v[20:21], v[28:29] op_sel_hi:[0,1,1]
	s_waitcnt lgkmcnt(13)
	v_pk_fma_f32 v[30:31], v[50:51], v[22:23], v[30:31] op_sel_hi:[0,1,1]
	v_pk_fma_f32 v[32:33], v[50:51], v[24:25], v[32:33] op_sel_hi:[0,1,1]
	s_waitcnt lgkmcnt(12)
	v_pk_fma_f32 v[18:19], v[50:51], v[194:195], v[26:27] op_sel:[1,0,0]
	v_pk_fma_f32 v[20:21], v[50:51], v[196:197], v[28:29] op_sel:[1,0,0]
	ds_read_b128 v[194:197], v41 offset:3072
	s_waitcnt lgkmcnt(12)
	v_pk_fma_f32 v[22:23], v[50:51], v[198:199], v[30:31] op_sel:[1,0,0]
	v_pk_fma_f32 v[24:25], v[50:51], v[200:201], v[32:33] op_sel:[1,0,0]
	ds_read_b128 v[198:201], v41 offset:3088
	s_waitcnt lgkmcnt(11)
	v_pk_fma_f32 v[26:27], v[42:43], v[202:203], v[18:19] op_sel_hi:[0,1,1]
	v_pk_fma_f32 v[28:29], v[42:43], v[204:205], v[20:21] op_sel_hi:[0,1,1]
	ds_read_b128 v[18:21], v41 offset:3328
	s_waitcnt lgkmcnt(11)
	v_pk_fma_f32 v[30:31], v[42:43], v[206:207], v[22:23] op_sel_hi:[0,1,1]
	v_pk_fma_f32 v[32:33], v[42:43], v[208:209], v[24:25] op_sel_hi:[0,1,1]
	ds_read_b128 v[22:25], v41 offset:3344
	ds_read2_b32 v[48:49], v44 offset0:14 offset1:15
	ds_read_b128 v[202:205], v41 offset:3584
	s_waitcnt lgkmcnt(13)
	ds_read_b128 v[206:209], v41 offset:3600
	v_pk_fma_f32 v[26:27], v[42:43], v[210:211], v[26:27] op_sel:[1,0,0]
	v_pk_fma_f32 v[28:29], v[42:43], v[212:213], v[28:29] op_sel:[1,0,0]
	s_waitcnt lgkmcnt(13)
	ds_read_b128 v[210:213], v41 offset:3840
	v_pk_fma_f32 v[30:31], v[42:43], v[214:215], v[30:31] op_sel:[1,0,0]
	v_pk_fma_f32 v[32:33], v[42:43], v[216:217], v[32:33] op_sel:[1,0,0]
	s_waitcnt lgkmcnt(13)
	ds_read_b128 v[214:217], v41 offset:3856
	s_waitcnt lgkmcnt(13)
	ds_read2_b32 v[42:43], v44 offset0:16 offset1:17
	v_pk_fma_f32 v[26:27], v[52:53], v[218:219], v[26:27] op_sel_hi:[0,1,1]
	v_pk_fma_f32 v[28:29], v[52:53], v[220:221], v[28:29] op_sel_hi:[0,1,1]
	s_waitcnt lgkmcnt(13)
	ds_read_b128 v[218:221], v41 offset:4096
	v_pk_fma_f32 v[30:31], v[52:53], v[222:223], v[30:31] op_sel_hi:[0,1,1]
	v_pk_fma_f32 v[32:33], v[52:53], v[224:225], v[32:33] op_sel_hi:[0,1,1]
	s_waitcnt lgkmcnt(13)
; __device__ __forceinline__ void chain_item(PP p, int jl, int sh, char* smem) {
;     ...
; #pragma unroll 8
;         for (int j0 = 0; j0 < 64; ++j0) {
;             const float sv = Sl[i * 65 + j0];
;             const f32x4 v0 = *(const f32x4*)(Pl + j0 * 64 + jq * 8), v1 = *(const f32x4*)(Pl + j0 * 64 + jq * 8 + 4);
;             acc[0] += sv * v0.x; acc[1] += sv * v0.y; acc[2] += sv * v0.z; acc[3] += sv * v0.w;
;             acc[4] += sv * v1.x; acc[5] += sv * v1.y; acc[6] += sv * v1.z; acc[7] += sv * v1.w;
;         }
	ds_read_b128 v[222:225], v41 offset:4112
	v_pk_fma_f32 v[26:27], v[52:53], v[226:227], v[26:27] op_sel:[1,0,0]
	v_pk_fma_f32 v[28:29], v[52:53], v[228:229], v[28:29] op_sel:[1,0,0]
	s_waitcnt lgkmcnt(13)
	ds_read_b128 v[226:229], v41 offset:4352
	v_pk_fma_f32 v[30:31], v[52:53], v[230:231], v[30:31] op_sel:[1,0,0]
	v_pk_fma_f32 v[32:33], v[52:53], v[232:233], v[32:33] op_sel:[1,0,0]
	s_waitcnt lgkmcnt(13)
	ds_read_b128 v[230:233], v41 offset:4368
	s_waitcnt lgkmcnt(13)
	ds_read2_b32 v[50:51], v44 offset0:18 offset1:19
	v_pk_fma_f32 v[26:27], v[46:47], v[194:195], v[26:27] op_sel_hi:[0,1,1]
	v_pk_fma_f32 v[28:29], v[46:47], v[196:197], v[28:29] op_sel_hi:[0,1,1]
	s_waitcnt lgkmcnt(13)
	ds_read_b128 v[194:197], v41 offset:4608
	v_pk_fma_f32 v[30:31], v[46:47], v[198:199], v[30:31] op_sel_hi:[0,1,1]
	v_pk_fma_f32 v[32:33], v[46:47], v[200:201], v[32:33] op_sel_hi:[0,1,1]
	s_waitcnt lgkmcnt(13)
	ds_read_b128 v[198:201], v41 offset:4624
	v_pk_fma_f32 v[26:27], v[46:47], v[18:19], v[26:27] op_sel:[1,0,0]
	v_pk_fma_f32 v[28:29], v[46:47], v[20:21], v[28:29] op_sel:[1,0,0]
	s_waitcnt lgkmcnt(13)
	v_pk_fma_f32 v[30:31], v[46:47], v[22:23], v[30:31] op_sel:[1,0,0]
	v_pk_fma_f32 v[32:33], v[46:47], v[24:25], v[32:33] op_sel:[1,0,0]
	s_waitcnt lgkmcnt(11)
	v_pk_fma_f32 v[26:27], v[48:49], v[202:203], v[26:27] op_sel_hi:[0,1,1]
	v_pk_fma_f32 v[28:29], v[48:49], v[204:205], v[28:29] op_sel_hi:[0,1,1]
	ds_read_b128 v[202:205], v41 offset:4864
	s_waitcnt lgkmcnt(11)
	v_pk_fma_f32 v[30:31], v[48:49], v[206:207], v[30:31] op_sel_hi:[0,1,1]
	v_pk_fma_f32 v[32:33], v[48:49], v[208:209], v[32:33] op_sel_hi:[0,1,1]
	ds_read_b128 v[206:209], v41 offset:4880
	ds_read2_b32 v[52:53], v44 offset0:20 offset1:21
	s_waitcnt lgkmcnt(12)
	v_pk_fma_f32 v[18:19], v[48:49], v[210:211], v[26:27] op_sel:[1,0,0]
	v_pk_fma_f32 v[20:21], v[48:49], v[212:213], v[28:29] op_sel:[1,0,0]
	ds_read_b128 v[210:213], v41 offset:5120
	s_waitcnt lgkmcnt(12)
	v_pk_fma_f32 v[22:23], v[48:49], v[214:215], v[30:31] op_sel:[1,0,0]
	v_pk_fma_f32 v[24:25], v[48:49], v[216:217], v[32:33] op_sel:[1,0,0]
	ds_read_b128 v[214:217], v41 offset:5136
	s_waitcnt lgkmcnt(11)
	v_pk_fma_f32 v[26:27], v[42:43], v[218:219], v[18:19] op_sel_hi:[0,1,1]
	v_pk_fma_f32 v[28:29], v[42:43], v[220:221], v[20:21] op_sel_hi:[0,1,1]
	ds_read_b128 v[18:21], v41 offset:5376
	s_waitcnt lgkmcnt(11)
	v_pk_fma_f32 v[30:31], v[42:43], v[222:223], v[22:23] op_sel_hi:[0,1,1]
	v_pk_fma_f32 v[32:33], v[42:43], v[224:225], v[24:25] op_sel_hi:[0,1,1]
	ds_read_b128 v[22:25], v41 offset:5392
	ds_read2_b32 v[46:47], v44 offset0:22 offset1:23
	ds_read_b128 v[218:221], v41 offset:5632
	s_waitcnt lgkmcnt(13)
	ds_read_b128 v[222:225], v41 offset:5648
	v_pk_fma_f32 v[26:27], v[42:43], v[226:227], v[26:27] op_sel:[1,0,0]
	v_pk_fma_f32 v[28:29], v[42:43], v[228:229], v[28:29] op_sel:[1,0,0]
	s_waitcnt lgkmcnt(13)
	ds_read_b128 v[226:229], v41 offset:5888
	v_pk_fma_f32 v[30:31], v[42:43], v[230:231], v[30:31] op_sel:[1,0,0]
	v_pk_fma_f32 v[32:33], v[42:43], v[232:233], v[32:33] op_sel:[1,0,0]
	s_waitcnt lgkmcnt(13)
	ds_read_b128 v[230:233], v41 offset:5904
	s_waitcnt lgkmcnt(13)
	ds_read2_b32 v[42:43], v44 offset0:24 offset1:25
	v_pk_fma_f32 v[26:27], v[50:51], v[194:195], v[26:27] op_sel_hi:[0,1,1]
	v_pk_fma_f32 v[28:29], v[50:51], v[196:197], v[28:29] op_sel_hi:[0,1,1]
	s_waitcnt lgkmcnt(13)
	ds_read_b128 v[194:197], v41 offset:6144
	v_pk_fma_f32 v[30:31], v[50:51], v[198:199], v[30:31] op_sel_hi:[0,1,1]
	v_pk_fma_f32 v[32:33], v[50:51], v[200:201], v[32:33] op_sel_hi:[0,1,1]
	s_waitcnt lgkmcnt(13)
	ds_read_b128 v[198:201], v41 offset:6160
	v_pk_fma_f32 v[26:27], v[50:51], v[202:203], v[26:27] op_sel:[1,0,0]
	v_pk_fma_f32 v[28:29], v[50:51], v[204:205], v[28:29] op_sel:[1,0,0]
	s_waitcnt lgkmcnt(13)
	ds_read_b128 v[202:205], v41 offset:6400
	v_pk_fma_f32 v[30:31], v[50:51], v[206:207], v[30:31] op_sel:[1,0,0]
	v_pk_fma_f32 v[32:33], v[50:51], v[208:209], v[32:33] op_sel:[1,0,0]
	s_waitcnt lgkmcnt(13)
	ds_read_b128 v[206:209], v41 offset:6416
	s_waitcnt lgkmcnt(13)
	ds_read2_b32 v[48:49], v44 offset0:26 offset1:27
	v_pk_fma_f32 v[26:27], v[52:53], v[210:211], v[26:27] op_sel_hi:[0,1,1]
	v_pk_fma_f32 v[28:29], v[52:53], v[212:213], v[28:29] op_sel_hi:[0,1,1]
	s_waitcnt lgkmcnt(13)
	ds_read_b128 v[210:213], v41 offset:6656
	v_pk_fma_f32 v[30:31], v[52:53], v[214:215], v[30:31] op_sel_hi:[0,1,1]
	v_pk_fma_f32 v[32:33], v[52:53], v[216:217], v[32:33] op_sel_hi:[0,1,1]
	s_waitcnt lgkmcnt(13)
	ds_read_b128 v[214:217], v41 offset:6672
	v_pk_fma_f32 v[26:27], v[52:53], v[18:19], v[26:27] op_sel:[1,0,0]
	v_pk_fma_f32 v[28:29], v[52:53], v[20:21], v[28:29] op_sel:[1,0,0]
	s_waitcnt lgkmcnt(13)
	v_pk_fma_f32 v[30:31], v[52:53], v[22:23], v[30:31] op_sel:[1,0,0]
	v_pk_fma_f32 v[32:33], v[52:53], v[24:25], v[32:33] op_sel:[1,0,0]
	s_waitcnt lgkmcnt(11)
	v_pk_fma_f32 v[26:27], v[46:47], v[218:219], v[26:27] op_sel_hi:[0,1,1]
	v_pk_fma_f32 v[28:29], v[46:47], v[220:221], v[28:29] op_sel_hi:[0,1,1]
	ds_read_b128 v[218:221], v41 offset:6912
	s_waitcnt lgkmcnt(11)
	v_pk_fma_f32 v[30:31], v[46:47], v[222:223], v[30:31] op_sel_hi:[0,1,1]
	v_pk_fma_f32 v[32:33], v[46:47], v[224:225], v[32:33] op_sel_hi:[0,1,1]
	ds_read_b128 v[222:225], v41 offset:6928
	ds_read2_b32 v[50:51], v44 offset0:28 offset1:29
	s_waitcnt lgkmcnt(12)
	v_pk_fma_f32 v[18:19], v[46:47], v[226:227], v[26:27] op_sel:[1,0,0]
	v_pk_fma_f32 v[20:21], v[46:47], v[228:229], v[28:29] op_sel:[1,0,0]
	ds_read_b128 v[226:229], v41 offset:7168
	s_waitcnt lgkmcnt(12)
	v_pk_fma_f32 v[22:23], v[46:47], v[230:231], v[30:31] op_sel:[1,0,0]
	v_pk_fma_f32 v[24:25], v[46:47], v[232:233], v[32:33] op_sel:[1,0,0]
	ds_read_b128 v[230:233], v41 offset:7184
	s_waitcnt lgkmcnt(11)
; __device__ __forceinline__ void chain_item(PP p, int jl, int sh, char* smem) {
;     ...
; #pragma unroll 8
;         for (int j0 = 0; j0 < 64; ++j0) {
;             const float sv = Sl[i * 65 + j0];
;             const f32x4 v0 = *(const f32x4*)(Pl + j0 * 64 + jq * 8), v1 = *(const f32x4*)(Pl + j0 * 64 + jq * 8 + 4);
;             acc[0] += sv * v0.x; acc[1] += sv * v0.y; acc[2] += sv * v0.z; acc[3] += sv * v0.w;
;             acc[4] += sv * v1.x; acc[5] += sv * v1.y; acc[6] += sv * v1.z; acc[7] += sv * v1.w;
;         }
	v_pk_fma_f32 v[26:27], v[42:43], v[194:195], v[18:19] op_sel_hi:[0,1,1]
	v_pk_fma_f32 v[28:29], v[42:43], v[196:197], v[20:21] op_sel_hi:[0,1,1]
	ds_read_b128 v[18:21], v41 offset:7424
	s_waitcnt lgkmcnt(11)
	v_pk_fma_f32 v[30:31], v[42:43], v[198:199], v[22:23] op_sel_hi:[0,1,1]
	v_pk_fma_f32 v[32:33], v[42:43], v[200:201], v[24:25] op_sel_hi:[0,1,1]
	ds_read_b128 v[22:25], v41 offset:7440
	ds_read2_b32 v[52:53], v44 offset0:30 offset1:31
	ds_read_b128 v[194:197], v41 offset:7680
	s_waitcnt lgkmcnt(13)
	ds_read_b128 v[198:201], v41 offset:7696
	v_pk_fma_f32 v[26:27], v[42:43], v[202:203], v[26:27] op_sel:[1,0,0]
	v_pk_fma_f32 v[28:29], v[42:43], v[204:205], v[28:29] op_sel:[1,0,0]
	s_waitcnt lgkmcnt(13)
	ds_read_b128 v[202:205], v41 offset:7936
	v_pk_fma_f32 v[30:31], v[42:43], v[206:207], v[30:31] op_sel:[1,0,0]
	v_pk_fma_f32 v[32:33], v[42:43], v[208:209], v[32:33] op_sel:[1,0,0]
	s_waitcnt lgkmcnt(13)
	ds_read_b128 v[206:209], v41 offset:7952
	s_waitcnt lgkmcnt(13)
	ds_read2_b32 v[42:43], v44 offset0:32 offset1:33
	v_pk_fma_f32 v[26:27], v[48:49], v[210:211], v[26:27] op_sel_hi:[0,1,1]
	v_pk_fma_f32 v[28:29], v[48:49], v[212:213], v[28:29] op_sel_hi:[0,1,1]
	s_waitcnt lgkmcnt(13)
	ds_read_b128 v[210:213], v41 offset:8192
	v_pk_fma_f32 v[30:31], v[48:49], v[214:215], v[30:31] op_sel_hi:[0,1,1]
	v_pk_fma_f32 v[32:33], v[48:49], v[216:217], v[32:33] op_sel_hi:[0,1,1]
	s_waitcnt lgkmcnt(13)
	ds_read_b128 v[214:217], v41 offset:8208
	v_pk_fma_f32 v[26:27], v[48:49], v[218:219], v[26:27] op_sel:[1,0,0]
	v_pk_fma_f32 v[28:29], v[48:49], v[220:221], v[28:29] op_sel:[1,0,0]
	s_waitcnt lgkmcnt(13)
	ds_read_b128 v[218:221], v41 offset:8448
	v_pk_fma_f32 v[30:31], v[48:49], v[222:223], v[30:31] op_sel:[1,0,0]
	v_pk_fma_f32 v[32:33], v[48:49], v[224:225], v[32:33] op_sel:[1,0,0]
	s_waitcnt lgkmcnt(13)
	ds_read_b128 v[222:225], v41 offset:8464
	s_waitcnt lgkmcnt(13)
	ds_read2_b32 v[46:47], v44 offset0:34 offset1:35
	v_pk_fma_f32 v[26:27], v[50:51], v[226:227], v[26:27] op_sel_hi:[0,1,1]
	v_pk_fma_f32 v[28:29], v[50:51], v[228:229], v[28:29] op_sel_hi:[0,1,1]
	s_waitcnt lgkmcnt(13)
	ds_read_b128 v[226:229], v41 offset:8704
	v_pk_fma_f32 v[30:31], v[50:51], v[230:231], v[30:31] op_sel_hi:[0,1,1]
	v_pk_fma_f32 v[32:33], v[50:51], v[232:233], v[32:33] op_sel_hi:[0,1,1]
	s_waitcnt lgkmcnt(13)
	ds_read_b128 v[230:233], v41 offset:8720
	v_pk_fma_f32 v[26:27], v[50:51], v[18:19], v[26:27] op_sel:[1,0,0]
	v_pk_fma_f32 v[28:29], v[50:51], v[20:21], v[28:29] op_sel:[1,0,0]
	s_waitcnt lgkmcnt(13)
	v_pk_fma_f32 v[30:31], v[50:51], v[22:23], v[30:31] op_sel:[1,0,0]
	v_pk_fma_f32 v[32:33], v[50:51], v[24:25], v[32:33] op_sel:[1,0,0]
	s_waitcnt lgkmcnt(11)
	v_pk_fma_f32 v[26:27], v[52:53], v[194:195], v[26:27] op_sel_hi:[0,1,1]
	v_pk_fma_f32 v[28:29], v[52:53], v[196:197], v[28:29] op_sel_hi:[0,1,1]
	ds_read_b128 v[194:197], v41 offset:8960
	s_waitcnt lgkmcnt(11)
	v_pk_fma_f32 v[30:31], v[52:53], v[198:199], v[30:31] op_sel_hi:[0,1,1]
	v_pk_fma_f32 v[32:33], v[52:53], v[200:201], v[32:33] op_sel_hi:[0,1,1]
	ds_read_b128 v[198:201], v41 offset:8976
	ds_read2_b32 v[48:49], v44 offset0:36 offset1:37
	s_waitcnt lgkmcnt(12)
	v_pk_fma_f32 v[18:19], v[52:53], v[202:203], v[26:27] op_sel:[1,0,0]
	v_pk_fma_f32 v[20:21], v[52:53], v[204:205], v[28:29] op_sel:[1,0,0]
	ds_read_b128 v[202:205], v41 offset:9216
	s_waitcnt lgkmcnt(12)
	v_pk_fma_f32 v[22:23], v[52:53], v[206:207], v[30:31] op_sel:[1,0,0]
	v_pk_fma_f32 v[24:25], v[52:53], v[208:209], v[32:33] op_sel:[1,0,0]
	ds_read_b128 v[206:209], v41 offset:9232
	s_waitcnt lgkmcnt(11)
	v_pk_fma_f32 v[26:27], v[42:43], v[210:211], v[18:19] op_sel_hi:[0,1,1]
	v_pk_fma_f32 v[28:29], v[42:43], v[212:213], v[20:21] op_sel_hi:[0,1,1]
	ds_read_b128 v[18:21], v41 offset:9472
	s_waitcnt lgkmcnt(11)
	v_pk_fma_f32 v[30:31], v[42:43], v[214:215], v[22:23] op_sel_hi:[0,1,1]
	v_pk_fma_f32 v[32:33], v[42:43], v[216:217], v[24:25] op_sel_hi:[0,1,1]
	ds_read_b128 v[22:25], v41 offset:9488
	ds_read2_b32 v[50:51], v44 offset0:38 offset1:39
	ds_read_b128 v[210:213], v41 offset:9728
	s_waitcnt lgkmcnt(13)
	ds_read_b128 v[214:217], v41 offset:9744
	v_pk_fma_f32 v[26:27], v[42:43], v[218:219], v[26:27] op_sel:[1,0,0]
	v_pk_fma_f32 v[28:29], v[42:43], v[220:221], v[28:29] op_sel:[1,0,0]
	s_waitcnt lgkmcnt(13)
	ds_read_b128 v[218:221], v41 offset:9984
	v_pk_fma_f32 v[30:31], v[42:43], v[222:223], v[30:31] op_sel:[1,0,0]
	v_pk_fma_f32 v[32:33], v[42:43], v[224:225], v[32:33] op_sel:[1,0,0]
	s_waitcnt lgkmcnt(13)
	ds_read_b128 v[222:225], v41 offset:10000
	s_waitcnt lgkmcnt(13)
	ds_read2_b32 v[42:43], v44 offset0:40 offset1:41
	v_pk_fma_f32 v[26:27], v[46:47], v[226:227], v[26:27] op_sel_hi:[0,1,1]
	v_pk_fma_f32 v[28:29], v[46:47], v[228:229], v[28:29] op_sel_hi:[0,1,1]
	s_waitcnt lgkmcnt(13)
	ds_read_b128 v[226:229], v41 offset:10240
	v_pk_fma_f32 v[30:31], v[46:47], v[230:231], v[30:31] op_sel_hi:[0,1,1]
	v_pk_fma_f32 v[32:33], v[46:47], v[232:233], v[32:33] op_sel_hi:[0,1,1]
	s_waitcnt lgkmcnt(13)
	ds_read_b128 v[230:233], v41 offset:10256
	v_pk_fma_f32 v[26:27], v[46:47], v[194:195], v[26:27] op_sel:[1,0,0]
	v_pk_fma_f32 v[28:29], v[46:47], v[196:197], v[28:29] op_sel:[1,0,0]
	s_waitcnt lgkmcnt(13)
	ds_read_b128 v[194:197], v41 offset:10496
	v_pk_fma_f32 v[30:31], v[46:47], v[198:199], v[30:31] op_sel:[1,0,0]
	v_pk_fma_f32 v[32:33], v[46:47], v[200:201], v[32:33] op_sel:[1,0,0]
	s_waitcnt lgkmcnt(13)
	ds_read_b128 v[198:201], v41 offset:10512
	s_waitcnt lgkmcnt(13)
	ds_read2_b32 v[52:53], v44 offset0:42 offset1:43
	v_pk_fma_f32 v[26:27], v[48:49], v[202:203], v[26:27] op_sel_hi:[0,1,1]
	v_pk_fma_f32 v[28:29], v[48:49], v[204:205], v[28:29] op_sel_hi:[0,1,1]
	s_waitcnt lgkmcnt(13)
; __device__ __forceinline__ void chain_item(PP p, int jl, int sh, char* smem) {
;     ...
; #pragma unroll 8
;         for (int j0 = 0; j0 < 64; ++j0) {
;             const float sv = Sl[i * 65 + j0];
;             const f32x4 v0 = *(const f32x4*)(Pl + j0 * 64 + jq * 8), v1 = *(const f32x4*)(Pl + j0 * 64 + jq * 8 + 4);
;             acc[0] += sv * v0.x; acc[1] += sv * v0.y; acc[2] += sv * v0.z; acc[3] += sv * v0.w;
;             acc[4] += sv * v1.x; acc[5] += sv * v1.y; acc[6] += sv * v1.z; acc[7] += sv * v1.w;
;         }
	ds_read_b128 v[202:205], v41 offset:10752
	v_pk_fma_f32 v[30:31], v[48:49], v[206:207], v[30:31] op_sel_hi:[0,1,1]
	v_pk_fma_f32 v[32:33], v[48:49], v[208:209], v[32:33] op_sel_hi:[0,1,1]
	s_waitcnt lgkmcnt(13)
	ds_read_b128 v[206:209], v41 offset:10768
	v_pk_fma_f32 v[26:27], v[48:49], v[18:19], v[26:27] op_sel:[1,0,0]
	v_pk_fma_f32 v[28:29], v[48:49], v[20:21], v[28:29] op_sel:[1,0,0]
	s_waitcnt lgkmcnt(13)
	v_pk_fma_f32 v[30:31], v[48:49], v[22:23], v[30:31] op_sel:[1,0,0]
	v_pk_fma_f32 v[32:33], v[48:49], v[24:25], v[32:33] op_sel:[1,0,0]
	s_waitcnt lgkmcnt(11)
	v_pk_fma_f32 v[26:27], v[50:51], v[210:211], v[26:27] op_sel_hi:[0,1,1]
	v_pk_fma_f32 v[28:29], v[50:51], v[212:213], v[28:29] op_sel_hi:[0,1,1]
	ds_read_b128 v[210:213], v41 offset:11008
	s_waitcnt lgkmcnt(11)
	v_pk_fma_f32 v[30:31], v[50:51], v[214:215], v[30:31] op_sel_hi:[0,1,1]
	v_pk_fma_f32 v[32:33], v[50:51], v[216:217], v[32:33] op_sel_hi:[0,1,1]
	ds_read_b128 v[214:217], v41 offset:11024
	ds_read2_b32 v[46:47], v44 offset0:44 offset1:45
	s_waitcnt lgkmcnt(12)
	v_pk_fma_f32 v[18:19], v[50:51], v[218:219], v[26:27] op_sel:[1,0,0]
	v_pk_fma_f32 v[20:21], v[50:51], v[220:221], v[28:29] op_sel:[1,0,0]
	ds_read_b128 v[218:221], v41 offset:11264
	s_waitcnt lgkmcnt(12)
	v_pk_fma_f32 v[22:23], v[50:51], v[222:223], v[30:31] op_sel:[1,0,0]
	v_pk_fma_f32 v[24:25], v[50:51], v[224:225], v[32:33] op_sel:[1,0,0]
	ds_read_b128 v[222:225], v41 offset:11280
	s_waitcnt lgkmcnt(11)
	v_pk_fma_f32 v[26:27], v[42:43], v[226:227], v[18:19] op_sel_hi:[0,1,1]
	v_pk_fma_f32 v[28:29], v[42:43], v[228:229], v[20:21] op_sel_hi:[0,1,1]
	ds_read_b128 v[18:21], v41 offset:11520
	s_waitcnt lgkmcnt(11)
	v_pk_fma_f32 v[30:31], v[42:43], v[230:231], v[22:23] op_sel_hi:[0,1,1]
	v_pk_fma_f32 v[32:33], v[42:43], v[232:233], v[24:25] op_sel_hi:[0,1,1]
	ds_read_b128 v[22:25], v41 offset:11536
	ds_read2_b32 v[48:49], v44 offset0:46 offset1:47
	ds_read_b128 v[226:229], v41 offset:11776
	s_waitcnt lgkmcnt(13)
	ds_read_b128 v[230:233], v41 offset:11792
	v_pk_fma_f32 v[26:27], v[42:43], v[194:195], v[26:27] op_sel:[1,0,0]
	v_pk_fma_f32 v[28:29], v[42:43], v[196:197], v[28:29] op_sel:[1,0,0]
	s_waitcnt lgkmcnt(13)
	ds_read_b128 v[194:197], v41 offset:12032
	v_pk_fma_f32 v[30:31], v[42:43], v[198:199], v[30:31] op_sel:[1,0,0]
	v_pk_fma_f32 v[32:33], v[42:43], v[200:201], v[32:33] op_sel:[1,0,0]
	s_waitcnt lgkmcnt(13)
	ds_read_b128 v[198:201], v41 offset:12048
	s_waitcnt lgkmcnt(13)
	ds_read2_b32 v[42:43], v44 offset0:48 offset1:49
	v_pk_fma_f32 v[26:27], v[52:53], v[202:203], v[26:27] op_sel_hi:[0,1,1]
	v_pk_fma_f32 v[28:29], v[52:53], v[204:205], v[28:29] op_sel_hi:[0,1,1]
	s_waitcnt lgkmcnt(13)
	ds_read_b128 v[202:205], v41 offset:12288
	v_pk_fma_f32 v[30:31], v[52:53], v[206:207], v[30:31] op_sel_hi:[0,1,1]
	v_pk_fma_f32 v[32:33], v[52:53], v[208:209], v[32:33] op_sel_hi:[0,1,1]
	s_waitcnt lgkmcnt(13)
	ds_read_b128 v[206:209], v41 offset:12304
	v_pk_fma_f32 v[26:27], v[52:53], v[210:211], v[26:27] op_sel:[1,0,0]
	v_pk_fma_f32 v[28:29], v[52:53], v[212:213], v[28:29] op_sel:[1,0,0]
	s_waitcnt lgkmcnt(13)
	ds_read_b128 v[210:213], v41 offset:12544
	v_pk_fma_f32 v[30:31], v[52:53], v[214:215], v[30:31] op_sel:[1,0,0]
	v_pk_fma_f32 v[32:33], v[52:53], v[216:217], v[32:33] op_sel:[1,0,0]
	s_waitcnt lgkmcnt(13)
	ds_read_b128 v[214:217], v41 offset:12560
	s_waitcnt lgkmcnt(13)
	ds_read2_b32 v[50:51], v44 offset0:50 offset1:51
	v_pk_fma_f32 v[26:27], v[46:47], v[218:219], v[26:27] op_sel_hi:[0,1,1]
	v_pk_fma_f32 v[28:29], v[46:47], v[220:221], v[28:29] op_sel_hi:[0,1,1]
	s_waitcnt lgkmcnt(13)
	ds_read_b128 v[218:221], v41 offset:12800
	v_pk_fma_f32 v[30:31], v[46:47], v[222:223], v[30:31] op_sel_hi:[0,1,1]
	v_pk_fma_f32 v[32:33], v[46:47], v[224:225], v[32:33] op_sel_hi:[0,1,1]
	s_waitcnt lgkmcnt(13)
	ds_read_b128 v[222:225], v41 offset:12816
	v_pk_fma_f32 v[26:27], v[46:47], v[18:19], v[26:27] op_sel:[1,0,0]
	v_pk_fma_f32 v[28:29], v[46:47], v[20:21], v[28:29] op_sel:[1,0,0]
	s_waitcnt lgkmcnt(13)
	v_pk_fma_f32 v[30:31], v[46:47], v[22:23], v[30:31] op_sel:[1,0,0]
	v_pk_fma_f32 v[32:33], v[46:47], v[24:25], v[32:33] op_sel:[1,0,0]
	s_waitcnt lgkmcnt(11)
	v_pk_fma_f32 v[26:27], v[48:49], v[226:227], v[26:27] op_sel_hi:[0,1,1]
	v_pk_fma_f32 v[28:29], v[48:49], v[228:229], v[28:29] op_sel_hi:[0,1,1]
	ds_read_b128 v[226:229], v41 offset:13056
	s_waitcnt lgkmcnt(11)
	v_pk_fma_f32 v[30:31], v[48:49], v[230:231], v[30:31] op_sel_hi:[0,1,1]
	v_pk_fma_f32 v[32:33], v[48:49], v[232:233], v[32:33] op_sel_hi:[0,1,1]
	ds_read_b128 v[230:233], v41 offset:13072
	ds_read2_b32 v[52:53], v44 offset0:52 offset1:53
	s_waitcnt lgkmcnt(12)
	v_pk_fma_f32 v[18:19], v[48:49], v[194:195], v[26:27] op_sel:[1,0,0]
	v_pk_fma_f32 v[20:21], v[48:49], v[196:197], v[28:29] op_sel:[1,0,0]
	ds_read_b128 v[194:197], v41 offset:13312
	s_waitcnt lgkmcnt(12)
	v_pk_fma_f32 v[22:23], v[48:49], v[198:199], v[30:31] op_sel:[1,0,0]
	v_pk_fma_f32 v[24:25], v[48:49], v[200:201], v[32:33] op_sel:[1,0,0]
	ds_read_b128 v[198:201], v41 offset:13328
	s_waitcnt lgkmcnt(11)
	v_pk_fma_f32 v[26:27], v[42:43], v[202:203], v[18:19] op_sel_hi:[0,1,1]
	v_pk_fma_f32 v[28:29], v[42:43], v[204:205], v[20:21] op_sel_hi:[0,1,1]
	ds_read_b128 v[18:21], v41 offset:13568
	s_waitcnt lgkmcnt(11)
	v_pk_fma_f32 v[30:31], v[42:43], v[206:207], v[22:23] op_sel_hi:[0,1,1]
	v_pk_fma_f32 v[32:33], v[42:43], v[208:209], v[24:25] op_sel_hi:[0,1,1]
	ds_read_b128 v[22:25], v41 offset:13584
	ds_read2_b32 v[46:47], v44 offset0:54 offset1:55
	ds_read_b128 v[202:205], v41 offset:13824
	s_waitcnt lgkmcnt(13)
; __device__ __forceinline__ void chain_item(PP p, int jl, int sh, char* smem) {
;     ...
; #pragma unroll 8
;         for (int j0 = 0; j0 < 64; ++j0) {
;             const float sv = Sl[i * 65 + j0];
;             const f32x4 v0 = *(const f32x4*)(Pl + j0 * 64 + jq * 8), v1 = *(const f32x4*)(Pl + j0 * 64 + jq * 8 + 4);
;             acc[0] += sv * v0.x; acc[1] += sv * v0.y; acc[2] += sv * v0.z; acc[3] += sv * v0.w;
;             acc[4] += sv * v1.x; acc[5] += sv * v1.y; acc[6] += sv * v1.z; acc[7] += sv * v1.w;
;         }
;         __syncthreads();
; #pragma unroll
;         for (int jj = 0; jj < 8; ++jj) Sl[i * 65 + jq * 8 + jj] = acc[jj];
;         float* Ub = Ub0 + (long)c * 4096;
	ds_read_b128 v[206:209], v41 offset:13840
	v_pk_fma_f32 v[26:27], v[42:43], v[210:211], v[26:27] op_sel:[1,0,0]
	v_pk_fma_f32 v[28:29], v[42:43], v[212:213], v[28:29] op_sel:[1,0,0]
	s_waitcnt lgkmcnt(13)
	ds_read_b128 v[210:213], v41 offset:14080
	v_pk_fma_f32 v[30:31], v[42:43], v[214:215], v[30:31] op_sel:[1,0,0]
	v_pk_fma_f32 v[32:33], v[42:43], v[216:217], v[32:33] op_sel:[1,0,0]
	s_waitcnt lgkmcnt(13)
	ds_read_b128 v[214:217], v41 offset:14096
	s_waitcnt lgkmcnt(13)
	ds_read2_b32 v[42:43], v44 offset0:56 offset1:57
	v_pk_fma_f32 v[26:27], v[50:51], v[218:219], v[26:27] op_sel_hi:[0,1,1]
	v_pk_fma_f32 v[28:29], v[50:51], v[220:221], v[28:29] op_sel_hi:[0,1,1]
	s_waitcnt lgkmcnt(13)
	ds_read_b128 v[218:221], v41 offset:14336
	v_pk_fma_f32 v[30:31], v[50:51], v[222:223], v[30:31] op_sel_hi:[0,1,1]
	v_pk_fma_f32 v[32:33], v[50:51], v[224:225], v[32:33] op_sel_hi:[0,1,1]
	s_waitcnt lgkmcnt(13)
	ds_read_b128 v[222:225], v41 offset:14352
	v_pk_fma_f32 v[26:27], v[50:51], v[226:227], v[26:27] op_sel:[1,0,0]
	v_pk_fma_f32 v[28:29], v[50:51], v[228:229], v[28:29] op_sel:[1,0,0]
	s_waitcnt lgkmcnt(13)
	ds_read_b128 v[226:229], v41 offset:14592
	v_pk_fma_f32 v[30:31], v[50:51], v[230:231], v[30:31] op_sel:[1,0,0]
	v_pk_fma_f32 v[32:33], v[50:51], v[232:233], v[32:33] op_sel:[1,0,0]
	s_waitcnt lgkmcnt(13)
	ds_read_b128 v[230:233], v41 offset:14608
	s_waitcnt lgkmcnt(13)
	ds_read2_b32 v[48:49], v44 offset0:58 offset1:59
	v_pk_fma_f32 v[26:27], v[52:53], v[194:195], v[26:27] op_sel_hi:[0,1,1]
	v_pk_fma_f32 v[28:29], v[52:53], v[196:197], v[28:29] op_sel_hi:[0,1,1]
	s_waitcnt lgkmcnt(13)
	ds_read_b128 v[194:197], v41 offset:14848
	v_pk_fma_f32 v[30:31], v[52:53], v[198:199], v[30:31] op_sel_hi:[0,1,1]
	v_pk_fma_f32 v[32:33], v[52:53], v[200:201], v[32:33] op_sel_hi:[0,1,1]
	s_waitcnt lgkmcnt(13)
	ds_read_b128 v[198:201], v41 offset:14864
	v_pk_fma_f32 v[26:27], v[52:53], v[18:19], v[26:27] op_sel:[1,0,0]
	v_pk_fma_f32 v[28:29], v[52:53], v[20:21], v[28:29] op_sel:[1,0,0]
	s_waitcnt lgkmcnt(13)
	v_pk_fma_f32 v[30:31], v[52:53], v[22:23], v[30:31] op_sel:[1,0,0]
	v_pk_fma_f32 v[32:33], v[52:53], v[24:25], v[32:33] op_sel:[1,0,0]
	s_waitcnt lgkmcnt(11)
	v_pk_fma_f32 v[26:27], v[46:47], v[202:203], v[26:27] op_sel_hi:[0,1,1]
	v_pk_fma_f32 v[28:29], v[46:47], v[204:205], v[28:29] op_sel_hi:[0,1,1]
	ds_read_b128 v[202:205], v41 offset:15104
	s_waitcnt lgkmcnt(11)
	v_pk_fma_f32 v[30:31], v[46:47], v[206:207], v[30:31] op_sel_hi:[0,1,1]
	v_pk_fma_f32 v[32:33], v[46:47], v[208:209], v[32:33] op_sel_hi:[0,1,1]
	ds_read_b128 v[206:209], v41 offset:15120
	ds_read2_b32 v[50:51], v44 offset0:60 offset1:61
	s_waitcnt lgkmcnt(12)
	v_pk_fma_f32 v[18:19], v[46:47], v[210:211], v[26:27] op_sel:[1,0,0]
	v_pk_fma_f32 v[20:21], v[46:47], v[212:213], v[28:29] op_sel:[1,0,0]
	ds_read_b128 v[210:213], v41 offset:15360
	s_waitcnt lgkmcnt(12)
	v_pk_fma_f32 v[22:23], v[46:47], v[214:215], v[30:31] op_sel:[1,0,0]
	v_pk_fma_f32 v[24:25], v[46:47], v[216:217], v[32:33] op_sel:[1,0,0]
	ds_read_b128 v[214:217], v41 offset:15376
	s_waitcnt lgkmcnt(11)
	v_pk_fma_f32 v[26:27], v[42:43], v[218:219], v[18:19] op_sel_hi:[0,1,1]
	v_pk_fma_f32 v[28:29], v[42:43], v[220:221], v[20:21] op_sel_hi:[0,1,1]
	ds_read_b128 v[18:21], v41 offset:15616
	s_waitcnt lgkmcnt(11)
	v_pk_fma_f32 v[30:31], v[42:43], v[222:223], v[22:23] op_sel_hi:[0,1,1]
	v_pk_fma_f32 v[32:33], v[42:43], v[224:225], v[24:25] op_sel_hi:[0,1,1]
	ds_read_b128 v[22:25], v41 offset:15632
	ds_read2_b32 v[52:53], v44 offset0:62 offset1:63
	ds_read_b128 v[218:221], v41 offset:15872
	s_waitcnt lgkmcnt(13)
	ds_read_b128 v[222:225], v41 offset:15888
	v_pk_fma_f32 v[26:27], v[42:43], v[226:227], v[26:27] op_sel:[1,0,0]
	v_pk_fma_f32 v[28:29], v[42:43], v[228:229], v[28:29] op_sel:[1,0,0]
	s_waitcnt lgkmcnt(13)
	ds_read_b128 v[226:229], v41 offset:16128
	v_pk_fma_f32 v[30:31], v[42:43], v[230:231], v[30:31] op_sel:[1,0,0]
	v_pk_fma_f32 v[32:33], v[42:43], v[232:233], v[32:33] op_sel:[1,0,0]
	s_waitcnt lgkmcnt(13)
	ds_read_b128 v[230:233], v41 offset:16144
	s_waitcnt lgkmcnt(13)
	v_pk_fma_f32 v[26:27], v[48:49], v[194:195], v[26:27] op_sel_hi:[0,1,1]
	v_pk_fma_f32 v[28:29], v[48:49], v[196:197], v[28:29] op_sel_hi:[0,1,1]
	s_waitcnt lgkmcnt(12)
	v_pk_fma_f32 v[30:31], v[48:49], v[198:199], v[30:31] op_sel_hi:[0,1,1]
	v_pk_fma_f32 v[32:33], v[48:49], v[200:201], v[32:33] op_sel_hi:[0,1,1]
	s_waitcnt lgkmcnt(11)
	v_pk_fma_f32 v[26:27], v[48:49], v[202:203], v[26:27] op_sel:[1,0,0]
	v_pk_fma_f32 v[28:29], v[48:49], v[204:205], v[28:29] op_sel:[1,0,0]
	s_waitcnt lgkmcnt(10)
	v_pk_fma_f32 v[30:31], v[48:49], v[206:207], v[30:31] op_sel:[1,0,0]
	v_pk_fma_f32 v[32:33], v[48:49], v[208:209], v[32:33] op_sel:[1,0,0]
	s_waitcnt lgkmcnt(8)
	v_pk_fma_f32 v[26:27], v[50:51], v[210:211], v[26:27] op_sel_hi:[0,1,1]
	v_pk_fma_f32 v[28:29], v[50:51], v[212:213], v[28:29] op_sel_hi:[0,1,1]
	s_waitcnt lgkmcnt(7)
	v_pk_fma_f32 v[30:31], v[50:51], v[214:215], v[30:31] op_sel_hi:[0,1,1]
	v_pk_fma_f32 v[32:33], v[50:51], v[216:217], v[32:33] op_sel_hi:[0,1,1]
	s_waitcnt lgkmcnt(6)
	v_pk_fma_f32 v[26:27], v[50:51], v[18:19], v[26:27] op_sel:[1,0,0]
	v_pk_fma_f32 v[28:29], v[50:51], v[20:21], v[28:29] op_sel:[1,0,0]
	s_waitcnt lgkmcnt(5)
	v_pk_fma_f32 v[30:31], v[50:51], v[22:23], v[30:31] op_sel:[1,0,0]
	v_pk_fma_f32 v[32:33], v[50:51], v[24:25], v[32:33] op_sel:[1,0,0]
	s_waitcnt lgkmcnt(3)
	v_pk_fma_f32 v[26:27], v[52:53], v[218:219], v[26:27] op_sel_hi:[0,1,1]
	v_pk_fma_f32 v[28:29], v[52:53], v[220:221], v[28:29] op_sel_hi:[0,1,1]
	s_waitcnt lgkmcnt(2)
	v_pk_fma_f32 v[30:31], v[52:53], v[222:223], v[30:31] op_sel_hi:[0,1,1]
	v_pk_fma_f32 v[32:33], v[52:53], v[224:225], v[32:33] op_sel_hi:[0,1,1]
	s_waitcnt lgkmcnt(1)
	v_pk_fma_f32 v[18:19], v[52:53], v[226:227], v[26:27] op_sel:[1,0,0]
	v_pk_fma_f32 v[20:21], v[52:53], v[228:229], v[28:29] op_sel:[1,0,0]
	s_waitcnt lgkmcnt(0)
	v_pk_fma_f32 v[22:23], v[52:53], v[230:231], v[30:31] op_sel:[1,0,0]
	v_pk_fma_f32 v[24:25], v[52:53], v[232:233], v[32:33] op_sel:[1,0,0]
	s_nop 0
	s_lshl_b32 s96, s6, 12
	v_lshl_add_u64 v[26:27], s[96:97], 2, v[34:35]
	s_barrier
; __device__ __forceinline__ void chain_item(PP p, int jl, int sh, char* smem) {
;     ...
;         __syncthreads();
; #pragma unroll
;         for (int jj = 0; jj < 8; ++jj) Sl[i * 65 + jq * 8 + jj] = acc[jj];
;         float* Ub = Ub0 + (long)c * 4096;
;         *(f32x4*)Ub = (f32x4){acc[0], acc[1], acc[2], acc[3]};
;         *(f32x4*)(Ub + 4) = (f32x4){acc[4], acc[5], acc[6], acc[7]};
;     }
;     const int b = sh >> 3, hd = sh & 7;
;     float* So = p->out + O_PRW + ((long)(jl * 2 + b) * 8 + hd) * 4096 + i * 64 + jq * 8;
;     *(f32x4*)So = (f32x4){acc[0], acc[1], acc[2], acc[3]};
;     *(f32x4*)(So + 4) = (f32x4){acc[4], acc[5], acc[6], acc[7]};
;     __syncthreads();
	ds_write2_b32 v37, v18, v19 offset1:1
	ds_write2_b32 v37, v20, v21 offset0:2 offset1:3
	ds_write2_b32 v37, v22, v23 offset0:4 offset1:5
	ds_write2_b32 v37, v24, v25 offset0:6 offset1:7
	global_store_dwordx4 v[26:27], v[18:21], off
	global_store_dwordx4 v[26:27], v[22:25], off offset:16
	s_waitcnt vmcnt(2)
	v_mov_b64_e32 v[32:33], v[16:17]
	v_mov_b64_e32 v[28:29], v[12:13]
	s_cmpk_eq_i32 s7, 0x80
	v_mov_b64_e32 v[30:31], v[14:15]
	v_mov_b64_e32 v[26:27], v[10:11]
	s_mov_b32 s6, s7
	s_cbranch_scc0 .LBB0_1736
	s_load_dwordx2 s[6:7], s[4:5], 0x128
	s_ashr_i32 s8, s10, 3
	v_readlane_b32 s12, v255, 29
	s_add_i32 s8, s8, s12
	s_ashr_i32 s9, s8, 31
	s_lshl_b64 s[8:9], s[8:9], 17
	s_waitcnt lgkmcnt(0)
	s_add_u32 s6, s6, s8
	s_addc_u32 s7, s7, s9
	s_lshl_b32 s8, s10, 14
	s_and_b32 s8, s8, 0x1c000
	s_add_u32 s6, s6, s8
	s_addc_u32 s7, s7, 0
	v_lshl_add_u64 v[2:3], v[2:3], 2, s[6:7]
	v_lshlrev_b32_e32 v0, 2, v36
	v_lshl_add_u64 v[2:3], v[2:3], 0, v[0:1]
	s_mov_b64 s[6:7], 0xcc00000
	v_lshl_add_u64 v[6:7], v[2:3], 0, s[6:7]
	v_add_co_u32_e32 v2, vcc, 0xcc00000, v2
	v_readlane_b32 s13, v255, 30
	s_nop 0
	v_addc_co_u32_e32 v3, vcc, 0, v3, vcc
	global_store_dwordx4 v[2:3], v[18:21], off
	global_store_dwordx4 v[6:7], v[22:25], off offset:16
	s_barrier
	s_movk_i32 s78, 0x100
	s_movk_i32 s79, 0x1000
	s_mov_b32 s96, 0x9000
	s_branch .LBB0_1688
